# GEMM K-loop: one static s_setprio 1 for the younger wave half (waves 4-7), per-phase priority flips deleted
# speedup vs baseline: 1.0109x; 1.0109x over previous
; #define PG8_STAGE(bufoff, gbase, voff) do { _Pragma("unroll") for (int _i = 0; _i < 2; ++_i) \
;         __builtin_amdgcn_global_load_lds((const unsigned*)((const char*)(gbase) + (voff)[_i]), (LAS unsigned*)(lds + (bufoff) + ldsw + _i * 8192), 16, 0, 0); } while (0)
; #define PG8_WAIT_V(n) asm volatile("s_waitcnt vmcnt(" #n ")" ::: "memory")
; #define PG8_BAR __builtin_amdgcn_s_barrier()
; template <class Epi>
; __device__ __forceinline__ void gemm_phase(LAS unsigned char* lds, const Gemm g, const StaticOrder& S, const Epi& E) {
;     int tid_ = threadIdx.x; asm volatile("" : "+v"(tid_));
;     const int tid = tid_, wid = __builtin_amdgcn_readfirstlane(tid >> 6), lane = tid & 63, wr = wid >> 2, wc = wid & 3, fr = lane & 15, fq = lane >> 4;
;     const int K = g.K, nt = K / BK, npass = g.A2 ? 2 : 1;
;     unsigned voffA[2], voffB[2];
; #pragma unroll
;     for (int i = 0; i < 2; ++i) { int R, C; stage_rc(tid * 16 + i * 8192, R, C); const int Rb = Epi::PERM ? ((R & ~31) + perm32(R & 31)) : R;
;         voffA[i] = (unsigned)(R * g.lda + C) * 2u; voffB[i] = (unsigned)(Rb * g.ldb + C) * 2u; }
;     const size_t kstep = (size_t)(BK * 2);
;     const size_t hstepA = (size_t)HALF * g.lda * 2, hstepB = (size_t)HALF * g.ldb * 2;
;     const size_t tstepA = 2 * hstepA, tstepB = 2 * hstepB;
;     const unsigned ldsw = (unsigned)wid * 1024u;
;     const int aoff = lds_byte(wr * 64 + fr, fq * 8), boff = lds_byte(wc * 32 + fr, fq * 8);
;     ...
;     Unit cur, nxt; int ui = 0;
;     if (!S.next(0, cur)) return;
;     f32x4 acc[2][2][4][2];
; #pragma unroll
;     for (int a = 0; a < 2; ++a)
; #pragma unroll
;         for (int b = 0; b < 2; ++b)
; #pragma unroll
;             for (int m = 0; m < 4; ++m)
; #pragma unroll
;                 for (int n = 0; n < 2; ++n) acc[a][b][m][n] = (f32x4){0.f, 0.f, 0.f, 0.f};
;     bf16x8 At[4][2], B0[2][2], B1[2][2];
;     const char* cA = (const char*)g.A + (size_t)cur.pm * tstepA; const char* cB = (const char*)g.Bt + (size_t)cur.pn * tstepB;
;     PG8_STAGE(PG8_SB(0, 0), cB, voffB); PG8_STAGE(PG8_SA(0, 0), cA, voffA); PG8_STAGE(PG8_SB(0, 1), cB + hstepB, voffB); PG8_STAGE(PG8_SA(0, 1), cA + hstepA, voffA);
;     if (wr == 1) PG8_BAR;
;     PG8_WAIT_V(4); PG8_BAR;
;     PG8_STAGE(PG8_SB(1, 0), cB + kstep, voffB); PG8_STAGE(PG8_SA(1, 0), cA + kstep, voffA); PG8_STAGE(PG8_SB(1, 1), cB + hstepB + kstep, voffB);
.LBB0_291:
	s_andn2_b64 vcc, exec, s[0:1]
	s_cbranch_vccnz .LBB0_587
	v_bfe_i32 v2, v11, 27, 1
	v_lshlrev_b32_e32 v0, 4, v11
	v_lshrrev_b32_e32 v2, 22, v2
	v_add_u32_e32 v2, v0, v2
	v_and_b32_e32 v2, 0xfffffc00, v2
	v_sub_u32_e32 v2, v0, v2
	v_ashrrev_i32_e32 v1, 31, v11
	v_lshrrev_b32_e32 v3, 4, v2
	v_lshrrev_b32_e32 v1, 26, v1
	v_bitop3_b32 v2, v3, v2, 32 bitop3:0x6c
	v_add_u32_e32 v1, v11, v1
	v_ashrrev_i32_e32 v4, 31, v2
	v_ashrrev_i32_e32 v1, 6, v1
	v_lshrrev_b32_e32 v4, 26, v4
	v_lshlrev_b32_e32 v3, 3, v1
	v_add_u32_e32 v4, v2, v4
	v_lshlrev_b32_e32 v1, 5, v1
	v_and_b32_e32 v9, 32, v1
	v_and_b32_e32 v1, 0xc0, v4
	v_and_b32_e32 v3, -16, v3
	v_ashrrev_i32_e32 v5, 6, v4
	v_sub_u32_e32 v1, v2, v1
	v_mov_b32_e32 v6, 1
	v_add_u32_e32 v3, v5, v3
	v_ashrrev_i16_sdwa v1, v6, sext(v1) dst_sel:DWORD dst_unused:UNUSED_PAD src0_sel:DWORD src1_sel:BYTE_0
	v_bfe_i32 v10, v1, 0, 16
	v_lshlrev_b32_e32 v2, 1, v3
	v_lshrrev_b32_e32 v4, 2, v3
	v_and_b32_e32 v5, 3, v5
	s_mov_b32 s1, 0x1fffe0
	v_add_u32_e32 v1, v9, v10
	v_and_b32_e32 v2, 24, v2
	v_and_b32_e32 v4, 4, v4
	v_and_or_b32 v5, v3, s1, v5
	v_mul_lo_u32 v12, v3, s4
	v_or3_b32 v2, v5, v4, v2
	v_add_lshl_u32 v180, v1, v12, 1
	v_lshlrev_b32_e32 v1, 1, v1
	v_add_u32_e32 v0, 0x2000, v0
	v_lshl_add_u32 v182, v2, 11, v1
	v_ashrrev_i32_e32 v1, 31, v0
	v_lshrrev_b32_e32 v1, 22, v1
	v_add_u32_e32 v1, v0, v1
	v_ashrrev_i32_e32 v1, 10, v1
	v_mul_i32_i24_e32 v2, 0x400, v1
	v_sub_u32_e32 v0, v0, v2
	v_lshrrev_b32_e32 v2, 4, v0
	v_bitop3_b32 v0, v2, v0, 32 bitop3:0x6c
	v_ashrrev_i32_e32 v3, 31, v0
	v_lshrrev_b32_e32 v3, 26, v3
	v_lshlrev_b32_e32 v2, 3, v1
	v_add_u32_e32 v3, v0, v3
	v_and_b32_e32 v2, -16, v2
	v_ashrrev_i32_e32 v4, 6, v3
	v_readlane_b32 s6, v255, 42
	v_add_u32_e32 v2, v4, v2
	v_lshlrev_b32_e32 v1, 5, v1
	v_and_b32_e32 v4, 3, v4
	v_and_b32_e32 v13, 32, v1
	v_and_b32_e32 v1, 0xc0, v3
	v_and_or_b32 v4, v2, s1, v4
	s_ashr_i32 s1, s6, 6
	s_ashr_i32 s53, s52, 31
	s_ashr_i32 s0, s6, 8
	v_sub_u32_e32 v0, v0, v1
	s_lshl_b32 s54, s4, 8
	s_lshl_b32 s56, s4, 9
	s_lshl_b32 s57, s1, 10
	s_lshl_b64 s[8:9], s[52:53], 19
	v_readlane_b32 s10, v255, 29
	v_ashrrev_i16_sdwa v0, v6, sext(v0) dst_sel:DWORD dst_unused:UNUSED_PAD src0_sel:DWORD src1_sel:BYTE_0
	v_readlane_b32 s11, v255, 30
	s_add_u32 s58, s10, s8
	v_bfe_i32 v14, v0, 0, 16
	v_lshlrev_b32_e32 v1, 1, v2
	v_lshrrev_b32_e32 v3, 2, v2
	s_addc_u32 s59, s11, s9
	s_add_i32 s12, s57, 0
	v_add_u32_e32 v0, v13, v14
	v_and_b32_e32 v1, 24, v1
	v_and_b32_e32 v3, 4, v3
	v_mul_lo_u32 v15, v2, s4
	s_add_i32 m0, s12, 0x10000
	v_or3_b32 v1, v4, v3, v1
	v_add_lshl_u32 v184, v0, v15, 1
	v_lshlrev_b32_e32 v0, 1, v0
	s_mul_i32 s6, s56, s73
	global_load_lds_dwordx4 v182, s[58:59]
	s_add_i32 m0, s12, 0x12000
	v_readlane_b32 s8, v255, 39
	v_lshl_add_u32 v186, v1, 11, v0
	s_mul_hi_i32 s4, s56, s73
	v_readlane_b32 s9, v255, 40
	s_add_u32 s60, s8, s6
	global_load_lds_dwordx4 v186, s[58:59]
	s_addc_u32 s61, s9, s4
	s_mov_b32 m0, s12
	s_add_i32 s13, s12, 0x2000
	global_load_lds_dwordx4 v180, s[60:61]
	s_mov_b32 m0, s13
	s_add_u32 s8, s58, 0x40000
	global_load_lds_dwordx4 v184, s[60:61]
	s_addc_u32 s9, s59, 0
	s_add_i32 m0, s12, 0x14000
	v_mov_b32_e32 v183, v177
	global_load_lds_dwordx4 v182, s[8:9]
	s_add_i32 m0, s12, 0x16000
	v_mov_b32_e32 v187, v177
	global_load_lds_dwordx4 v186, s[8:9]
	s_add_u32 s8, s60, s54
	s_addc_u32 s9, s61, 0
	s_add_i32 s4, s12, 0x4000
	s_mov_b32 m0, s4
	s_add_i32 s70, s12, 0x6000
	global_load_lds_dwordx4 v180, s[8:9]
	s_mov_b32 m0, s70
	v_mov_b32_e32 v181, v177
	global_load_lds_dwordx4 v184, s[8:9]
	v_mov_b32_e32 v185, v177
	s_mov_b32 s55, s37
	v_lshl_add_u64 v[6:7], s[58:59], 0, v[182:183]
	v_lshl_add_u64 v[4:5], s[58:59], 0, v[186:187]
	v_lshl_add_u64 v[2:3], s[60:61], 0, v[180:181]
	s_cmp_lg_u32 s0, 1
	v_lshl_add_u64 v[0:1], s[60:61], 0, v[184:185]
	s_mov_b32 s24, 0x3db504f3
	s_cbranch_scc1 .LBB0_294
	s_barrier
	s_setprio 1

; #define PG8_STAGE(bufoff, gbase, voff) do { _Pragma("unroll") for (int _i = 0; _i < 2; ++_i) \
;         __builtin_amdgcn_global_load_lds((const unsigned*)((const char*)(gbase) + (voff)[_i]), (LAS unsigned*)(lds + (bufoff) + ldsw + _i * 8192), 16, 0, 0); } while (0)
; #define PG8_LDA(dst, b, h) do { _Pragma("unroll") for (int m = 0; m < 4; ++m) _Pragma("unroll") for (int k = 0; k < 2; ++k) dst[m][k] = *(const LAS bf16x8*)(lds + PG8_SA(b, h) + aoff + m * 2048 + k * 1024); } while (0)
; #define PG8_LDB(dst, b, h) do { _Pragma("unroll") for (int n = 0; n < 2; ++n) _Pragma("unroll") for (int k = 0; k < 2; ++k) dst[n][k] = *(const LAS bf16x8*)(lds + PG8_SB(b, h) + boff + n * 2048 + k * 1024); } while (0)
; #define PG8_MMA(ai, bj, At, Bt) do { __builtin_amdgcn_s_setprio(1); _Pragma("unroll") for (int m = 0; m < 4; ++m) _Pragma("unroll") for (int n = 0; n < 2; ++n) _Pragma("unroll") for (int k = 0; k < 2; ++k) \
;         acc[ai][bj][m][n] = __builtin_amdgcn_mfma_f32_16x16x32_bf16(Bt[n][k], At[m][k], acc[ai][bj][m][n], 0, 0, 0); __builtin_amdgcn_s_setprio(0); } while (0)
; #define PG8_WAIT_V(n) asm volatile("s_waitcnt vmcnt(" #n ")" ::: "memory")
; #define PG8_WAIT_L(n) asm volatile("s_waitcnt lgkmcnt(" #n ")" ::: "memory")
; template <class Epi>
; __device__ __forceinline__ void gemm_phase(LAS unsigned char* lds, const Gemm g, const StaticOrder& S, const Epi& E) {
;     ...
;         for (int t = 0; t < nt; t += 2) {
;             const bool last = (t == nt - 2);
;             const char* a1 = cA + (size_t)(t + 1) * kstep;
;             const char* a2 = last ? nA : cA + (size_t)(t + 2) * kstep; const char* b2 = last ? nB : cB + (size_t)(t + 2) * kstep;
;             const char* a3 = a2 + kstep; const char* b3 = b2 + kstep;
;             PG8_LDB(B0, 0, 0); PG8_SCHED; PG8_LDA(At, 0, 0); PG8_STAGE(PG8_SA(1, 1), a1 + hstepA, voffA);
;             PG8_WAIT_L(8); PG8_BAR; PG8_WAIT_L(0); PG8_MMA(0, 0, At, B0); PG8_BAR; PG8_SCHED;
;             PG8_LDB(B1, 0, 1); PG8_STAGE(PG8_SB(0, 0), b2, voffB);
;             PG8_BAR; PG8_WAIT_L(0); PG8_MMA(0, 1, At, B1); PG8_BAR;
;             PG8_LDA(At, 0, 1); PG8_STAGE(PG8_SA(0, 0), a2, voffA);
;             PG8_BAR; PG8_WAIT_L(0); PG8_MMA(1, 0, At, B0); PG8_BAR; PG8_SCHED;
;             PG8_STAGE(PG8_SB(0, 1), b2 + hstepB, voffB);
;             PG8_WAIT_V(6); PG8_BAR; PG8_MMA(1, 1, At, B1); PG8_BAR;
.LBB0_302:
	s_add_u32 s10, s46, s64
	s_addc_u32 s11, s47, s65
	s_add_u32 s100, s10, 0x80
	s_addc_u32 s101, s11, 0
	s_add_u32 s10, s10, 0x100
	s_addc_u32 s11, s11, 0
	s_add_u32 s66, vcc_lo, s64
	s_addc_u32 s67, vcc_hi, s65
	s_add_i32 s72, 0, 0x10000
	v_add_u32_e32 v144, s72, v252
	ds_read_b128 v[132:135], v144
	ds_read_b128 v[136:139], v144 offset:1024
	ds_read_b128 v[140:143], v144 offset:2048
	ds_read_b128 v[144:147], v144 offset:3072
	s_cmpk_eq_i32 s64, 0x700
	s_cselect_b32 s69, s61, s11
	s_cselect_b32 s68, s60, s10
	s_cselect_b32 s67, s59, s67
	s_cselect_b32 s66, s58, s66
	s_add_i32 m0, s12, 0xc000
	ds_read_b128 v[148:151], v241
	ds_read_b128 v[152:155], v241 offset:1024
	ds_read_b128 v[156:159], v241 offset:2048
	ds_read_b128 v[160:163], v241 offset:3072
	ds_read_b128 v[164:167], v241 offset:4096
	ds_read_b128 v[168:171], v241 offset:5120
	ds_read_b128 v[172:175], v241 offset:6144
	ds_read_b128 v[192:195], v241 offset:7168
	global_load_lds_dwordx4 v190, s[100:101]
	s_add_i32 m0, s12, 0xe000
	s_nop 0
	global_load_lds_dwordx4 v188, s[100:101]
	s_waitcnt lgkmcnt(8)
	s_barrier
	s_waitcnt lgkmcnt(0)
	s_waitcnt lgkmcnt(0)
	v_mfma_f32_16x16x32_bf16 v[124:127], v[132:135], v[148:151], v[124:127]
	v_mfma_f32_16x16x32_bf16 v[120:123], v[140:143], v[148:151], v[120:123]
	v_mfma_f32_16x16x32_bf16 v[116:119], v[132:135], v[156:159], v[116:119]
	v_mfma_f32_16x16x32_bf16 v[112:115], v[140:143], v[156:159], v[112:115]
	v_mfma_f32_16x16x32_bf16 v[108:111], v[132:135], v[164:167], v[108:111]
	v_mfma_f32_16x16x32_bf16 v[104:107], v[140:143], v[164:167], v[104:107]
	v_mfma_f32_16x16x32_bf16 v[100:103], v[132:135], v[172:175], v[100:103]
	v_mfma_f32_16x16x32_bf16 v[96:99], v[140:143], v[172:175], v[96:99]
	v_mfma_f32_16x16x32_bf16 v[124:127], v[136:139], v[152:155], v[124:127]
	v_mfma_f32_16x16x32_bf16 v[120:123], v[144:147], v[152:155], v[120:123]
	v_mfma_f32_16x16x32_bf16 v[116:119], v[136:139], v[160:163], v[116:119]
	v_mfma_f32_16x16x32_bf16 v[112:115], v[144:147], v[160:163], v[112:115]
	v_mfma_f32_16x16x32_bf16 v[108:111], v[136:139], v[168:171], v[108:111]
	v_mfma_f32_16x16x32_bf16 v[104:107], v[144:147], v[168:171], v[104:107]
	v_mfma_f32_16x16x32_bf16 v[100:103], v[136:139], v[192:195], v[100:103]
	v_mfma_f32_16x16x32_bf16 v[96:99], v[144:147], v[192:195], v[96:99]
	s_barrier
	s_add_i32 s40, 0, 0x14000
	s_add_i32 s10, s72, s57
	v_add_u32_e32 v176, s40, v252
	s_mov_b32 m0, s10
	ds_read_b128 v[196:199], v176
	ds_read_b128 v[200:203], v176 offset:1024
	ds_read_b128 v[204:207], v176 offset:2048
	ds_read_b128 v[208:211], v176 offset:3072
	global_load_lds_dwordx4 v182, s[66:67]
	s_add_i32 m0, s10, 0x2000
	s_nop 0
	global_load_lds_dwordx4 v186, s[66:67]
	s_barrier
	s_waitcnt lgkmcnt(0)
	s_waitcnt lgkmcnt(0)
	v_mfma_f32_16x16x32_bf16 v[60:63], v[196:199], v[148:151], v[60:63]
	v_mfma_f32_16x16x32_bf16 v[56:59], v[204:207], v[148:151], v[56:59]
	v_mfma_f32_16x16x32_bf16 v[52:55], v[196:199], v[156:159], v[52:55]
	v_mfma_f32_16x16x32_bf16 v[48:51], v[204:207], v[156:159], v[48:51]
	v_mfma_f32_16x16x32_bf16 v[44:47], v[196:199], v[164:167], v[44:47]
	v_mfma_f32_16x16x32_bf16 v[40:43], v[204:207], v[164:167], v[40:43]
	v_mfma_f32_16x16x32_bf16 v[36:39], v[196:199], v[172:175], v[36:39]
	v_mfma_f32_16x16x32_bf16 v[32:35], v[204:207], v[172:175], v[32:35]
	v_mfma_f32_16x16x32_bf16 v[60:63], v[200:203], v[152:155], v[60:63]
	v_mfma_f32_16x16x32_bf16 v[56:59], v[208:211], v[152:155], v[56:59]
	v_mfma_f32_16x16x32_bf16 v[52:55], v[200:203], v[160:163], v[52:55]
	v_mfma_f32_16x16x32_bf16 v[48:51], v[208:211], v[160:163], v[48:51]
	v_mfma_f32_16x16x32_bf16 v[44:47], v[200:203], v[168:171], v[44:47]
	v_mfma_f32_16x16x32_bf16 v[40:43], v[208:211], v[168:171], v[40:43]
	v_mfma_f32_16x16x32_bf16 v[36:39], v[200:203], v[192:195], v[36:39]
	v_mfma_f32_16x16x32_bf16 v[32:35], v[208:211], v[192:195], v[32:35]
	s_mov_b32 m0, s12
	s_barrier
	ds_read_b128 v[148:151], v241 offset:16384
	ds_read_b128 v[152:155], v241 offset:17408
	ds_read_b128 v[156:159], v241 offset:18432
	ds_read_b128 v[160:163], v241 offset:19456
	ds_read_b128 v[164:167], v241 offset:20480
	ds_read_b128 v[168:171], v241 offset:21504
	ds_read_b128 v[172:175], v241 offset:22528
	ds_read_b128 v[192:195], v241 offset:23552
	global_load_lds_dwordx4 v180, s[68:69]
	s_mov_b32 m0, s13
	s_nop 0
	global_load_lds_dwordx4 v184, s[68:69]
	s_barrier
	s_waitcnt lgkmcnt(0)
	s_waitcnt lgkmcnt(0)
	v_mfma_f32_16x16x32_bf16 v[92:95], v[132:135], v[148:151], v[92:95]
	v_mfma_f32_16x16x32_bf16 v[88:91], v[140:143], v[148:151], v[88:91]
	v_mfma_f32_16x16x32_bf16 v[84:87], v[132:135], v[156:159], v[84:87]
	v_mfma_f32_16x16x32_bf16 v[80:83], v[140:143], v[156:159], v[80:83]
	v_mfma_f32_16x16x32_bf16 v[76:79], v[132:135], v[164:167], v[76:79]
	v_mfma_f32_16x16x32_bf16 v[72:75], v[140:143], v[164:167], v[72:75]
	v_mfma_f32_16x16x32_bf16 v[68:71], v[132:135], v[172:175], v[68:71]
	v_mfma_f32_16x16x32_bf16 v[64:67], v[140:143], v[172:175], v[64:67]
	v_mfma_f32_16x16x32_bf16 v[92:95], v[136:139], v[152:155], v[92:95]
	v_mfma_f32_16x16x32_bf16 v[88:91], v[144:147], v[152:155], v[88:91]
	v_mfma_f32_16x16x32_bf16 v[84:87], v[136:139], v[160:163], v[84:87]
	v_mfma_f32_16x16x32_bf16 v[80:83], v[144:147], v[160:163], v[80:83]
	v_mfma_f32_16x16x32_bf16 v[76:79], v[136:139], v[168:171], v[76:79]
	v_mfma_f32_16x16x32_bf16 v[72:75], v[144:147], v[168:171], v[72:75]
	v_mfma_f32_16x16x32_bf16 v[68:71], v[136:139], v[192:195], v[68:71]
	v_mfma_f32_16x16x32_bf16 v[64:67], v[144:147], v[192:195], v[64:67]
	s_barrier
	s_add_u32 s10, s66, 0x40000
	s_addc_u32 s11, s67, 0
	s_add_i32 s40, s40, s57
	s_mov_b32 m0, s40
	s_nop 0
	global_load_lds_dwordx4 v182, s[10:11]
	s_add_i32 m0, s40, 0x2000
	s_nop 0
	global_load_lds_dwordx4 v186, s[10:11]
	s_waitcnt vmcnt(6)
	s_barrier
; #define PG8_STAGE(bufoff, gbase, voff) do { _Pragma("unroll") for (int _i = 0; _i < 2; ++_i) \
;         __builtin_amdgcn_global_load_lds((const unsigned*)((const char*)(gbase) + (voff)[_i]), (LAS unsigned*)(lds + (bufoff) + ldsw + _i * 8192), 16, 0, 0); } while (0)
; #define PG8_LDA(dst, b, h) do { _Pragma("unroll") for (int m = 0; m < 4; ++m) _Pragma("unroll") for (int k = 0; k < 2; ++k) dst[m][k] = *(const LAS bf16x8*)(lds + PG8_SA(b, h) + aoff + m * 2048 + k * 1024); } while (0)
; #define PG8_LDB(dst, b, h) do { _Pragma("unroll") for (int n = 0; n < 2; ++n) _Pragma("unroll") for (int k = 0; k < 2; ++k) dst[n][k] = *(const LAS bf16x8*)(lds + PG8_SB(b, h) + boff + n * 2048 + k * 1024); } while (0)
; #define PG8_MMA(ai, bj, At, Bt) do { __builtin_amdgcn_s_setprio(1); _Pragma("unroll") for (int m = 0; m < 4; ++m) _Pragma("unroll") for (int n = 0; n < 2; ++n) _Pragma("unroll") for (int k = 0; k < 2; ++k) \
;         acc[ai][bj][m][n] = __builtin_amdgcn_mfma_f32_16x16x32_bf16(Bt[n][k], At[m][k], acc[ai][bj][m][n], 0, 0, 0); __builtin_amdgcn_s_setprio(0); } while (0)
; #define PG8_WAIT_V(n) asm volatile("s_waitcnt vmcnt(" #n ")" ::: "memory")
; #define PG8_WAIT_L(n) asm volatile("s_waitcnt lgkmcnt(" #n ")" ::: "memory")
; #define PG8_BAR __builtin_amdgcn_s_barrier()
; #define PG8_SCHED __builtin_amdgcn_sched_barrier(0)
; template <class Epi>
; __device__ __forceinline__ void gemm_phase(LAS unsigned char* lds, const Gemm g, const StaticOrder& S, const Epi& E) {
;     ...
;             PG8_WAIT_V(6); PG8_BAR; PG8_MMA(1, 1, At, B1); PG8_BAR;
;             PG8_LDB(B0, 1, 0); PG8_SCHED; PG8_LDA(At, 1, 0); PG8_STAGE(PG8_SA(0, 1), a2 + hstepA, voffA);
;             PG8_WAIT_L(8); PG8_BAR; PG8_WAIT_L(0); PG8_MMA(0, 0, At, B0); PG8_BAR; PG8_SCHED;
;             PG8_LDB(B1, 1, 1); PG8_STAGE(PG8_SB(1, 0), b3, voffB);
;             PG8_BAR; PG8_WAIT_L(0); PG8_MMA(0, 1, At, B1); PG8_BAR;
;             PG8_LDA(At, 1, 1); PG8_STAGE(PG8_SA(1, 0), a3, voffA);
;             PG8_BAR; PG8_WAIT_L(0); PG8_MMA(1, 0, At, B0); PG8_BAR; PG8_SCHED;
	v_mfma_f32_16x16x32_bf16 v[28:31], v[196:199], v[148:151], v[28:31]
	v_mfma_f32_16x16x32_bf16 v[24:27], v[204:207], v[148:151], v[24:27]
	v_mfma_f32_16x16x32_bf16 v[20:23], v[196:199], v[156:159], v[20:23]
	v_mfma_f32_16x16x32_bf16 v[16:19], v[204:207], v[156:159], v[16:19]
	v_mfma_f32_16x16x32_bf16 v[12:15], v[196:199], v[164:167], v[12:15]
	v_mfma_f32_16x16x32_bf16 v[8:11], v[204:207], v[164:167], v[8:11]
	v_mfma_f32_16x16x32_bf16 v[4:7], v[196:199], v[172:175], v[4:7]
	v_mfma_f32_16x16x32_bf16 v[0:3], v[204:207], v[172:175], v[0:3]
	v_mfma_f32_16x16x32_bf16 v[28:31], v[200:203], v[152:155], v[28:31]
	v_mfma_f32_16x16x32_bf16 v[24:27], v[208:211], v[152:155], v[24:27]
	v_mfma_f32_16x16x32_bf16 v[20:23], v[200:203], v[160:163], v[20:23]
	v_mfma_f32_16x16x32_bf16 v[16:19], v[208:211], v[160:163], v[16:19]
	v_mfma_f32_16x16x32_bf16 v[12:15], v[200:203], v[168:171], v[12:15]
	v_mfma_f32_16x16x32_bf16 v[8:11], v[208:211], v[168:171], v[8:11]
	v_mfma_f32_16x16x32_bf16 v[4:7], v[200:203], v[192:195], v[4:7]
	v_mfma_f32_16x16x32_bf16 v[0:3], v[208:211], v[192:195], v[0:3]
	s_add_i32 s40, 0, 0x18000
	v_add_u32_e32 v144, s40, v252
	s_barrier
	ds_read_b128 v[132:135], v144
	ds_read_b128 v[136:139], v144 offset:1024
	ds_read_b128 v[140:143], v144 offset:2048
	ds_read_b128 v[144:147], v144 offset:3072
	s_add_u32 s10, s68, s54
	s_addc_u32 s11, s69, 0
	s_mov_b32 m0, s4
	ds_read_b128 v[148:151], v241 offset:32768
	ds_read_b128 v[152:155], v241 offset:33792
	ds_read_b128 v[156:159], v241 offset:34816
	ds_read_b128 v[160:163], v241 offset:35840
	ds_read_b128 v[164:167], v241 offset:36864
	ds_read_b128 v[168:171], v241 offset:37888
	ds_read_b128 v[172:175], v241 offset:38912
	ds_read_b128 v[192:195], v241 offset:39936
	global_load_lds_dwordx4 v180, s[10:11]
	s_mov_b32 m0, s70
	s_nop 0
	global_load_lds_dwordx4 v184, s[10:11]
	s_waitcnt lgkmcnt(8)
	s_barrier
	s_waitcnt lgkmcnt(0)
	s_waitcnt lgkmcnt(0)
	v_mfma_f32_16x16x32_bf16 v[124:127], v[132:135], v[148:151], v[124:127]
	v_mfma_f32_16x16x32_bf16 v[120:123], v[140:143], v[148:151], v[120:123]
	v_mfma_f32_16x16x32_bf16 v[116:119], v[132:135], v[156:159], v[116:119]
	v_mfma_f32_16x16x32_bf16 v[112:115], v[140:143], v[156:159], v[112:115]
	v_mfma_f32_16x16x32_bf16 v[108:111], v[132:135], v[164:167], v[108:111]
	v_mfma_f32_16x16x32_bf16 v[104:107], v[140:143], v[164:167], v[104:107]
	v_mfma_f32_16x16x32_bf16 v[100:103], v[132:135], v[172:175], v[100:103]
	v_mfma_f32_16x16x32_bf16 v[96:99], v[140:143], v[172:175], v[96:99]
	v_mfma_f32_16x16x32_bf16 v[124:127], v[136:139], v[152:155], v[124:127]
	v_mfma_f32_16x16x32_bf16 v[120:123], v[144:147], v[152:155], v[120:123]
	v_mfma_f32_16x16x32_bf16 v[116:119], v[136:139], v[160:163], v[116:119]
	v_mfma_f32_16x16x32_bf16 v[112:115], v[144:147], v[160:163], v[112:115]
	v_mfma_f32_16x16x32_bf16 v[108:111], v[136:139], v[168:171], v[108:111]
	v_mfma_f32_16x16x32_bf16 v[104:107], v[144:147], v[168:171], v[104:107]
	v_mfma_f32_16x16x32_bf16 v[100:103], v[136:139], v[192:195], v[100:103]
	v_mfma_f32_16x16x32_bf16 v[96:99], v[144:147], v[192:195], v[96:99]
	s_barrier
	s_add_i32 s41, 0, 0x1c000
	s_add_i32 s10, s40, s57
	v_add_u32_e32 v176, s41, v252
	s_add_u32 s100, s66, 0x80
	s_addc_u32 s101, s67, 0
	s_mov_b32 m0, s10
	ds_read_b128 v[196:199], v176
	ds_read_b128 v[200:203], v176 offset:1024
	ds_read_b128 v[204:207], v176 offset:2048
	ds_read_b128 v[208:211], v176 offset:3072
	global_load_lds_dwordx4 v182, s[100:101]
	s_add_i32 m0, s10, 0x2000
	s_nop 0
	global_load_lds_dwordx4 v186, s[100:101]
	s_barrier
	s_waitcnt lgkmcnt(0)
	s_waitcnt lgkmcnt(0)
	v_mfma_f32_16x16x32_bf16 v[60:63], v[196:199], v[148:151], v[60:63]
	v_mfma_f32_16x16x32_bf16 v[56:59], v[204:207], v[148:151], v[56:59]
	v_mfma_f32_16x16x32_bf16 v[52:55], v[196:199], v[156:159], v[52:55]
	v_mfma_f32_16x16x32_bf16 v[48:51], v[204:207], v[156:159], v[48:51]
	v_mfma_f32_16x16x32_bf16 v[44:47], v[196:199], v[164:167], v[44:47]
	v_mfma_f32_16x16x32_bf16 v[40:43], v[204:207], v[164:167], v[40:43]
	v_mfma_f32_16x16x32_bf16 v[36:39], v[196:199], v[172:175], v[36:39]
	v_mfma_f32_16x16x32_bf16 v[32:35], v[204:207], v[172:175], v[32:35]
	v_mfma_f32_16x16x32_bf16 v[60:63], v[200:203], v[152:155], v[60:63]
	v_mfma_f32_16x16x32_bf16 v[56:59], v[208:211], v[152:155], v[56:59]
	v_mfma_f32_16x16x32_bf16 v[52:55], v[200:203], v[160:163], v[52:55]
	v_mfma_f32_16x16x32_bf16 v[48:51], v[208:211], v[160:163], v[48:51]
	v_mfma_f32_16x16x32_bf16 v[44:47], v[200:203], v[168:171], v[44:47]
	v_mfma_f32_16x16x32_bf16 v[40:43], v[208:211], v[168:171], v[40:43]
	v_mfma_f32_16x16x32_bf16 v[36:39], v[200:203], v[192:195], v[36:39]
	v_mfma_f32_16x16x32_bf16 v[32:35], v[208:211], v[192:195], v[32:35]
	s_mov_b32 m0, s6
	s_add_u32 s100, s68, 0x80
	s_addc_u32 s101, s69, 0
	s_barrier
	ds_read_b128 v[148:151], v241 offset:49152
	ds_read_b128 v[152:155], v241 offset:50176
	ds_read_b128 v[156:159], v241 offset:51200
	ds_read_b128 v[160:163], v241 offset:52224
	ds_read_b128 v[164:167], v241 offset:53248
	ds_read_b128 v[168:171], v241 offset:54272
	ds_read_b128 v[172:175], v241 offset:55296
	ds_read_b128 v[192:195], v241 offset:56320
	global_load_lds_dwordx4 v180, s[100:101]
	s_mov_b32 m0, s78
	s_nop 0
	global_load_lds_dwordx4 v184, s[100:101]
	s_barrier
; __device__ __forceinline__ float bf_lo(unsigned u) { return __uint_as_float(u << 16); }
; __device__ __forceinline__ float bf_hi(unsigned u) { return __uint_as_float(u & 0xffff0000u); }
; #define PG8_STAGE(bufoff, gbase, voff) do { _Pragma("unroll") for (int _i = 0; _i < 2; ++_i) \
;         __builtin_amdgcn_global_load_lds((const unsigned*)((const char*)(gbase) + (voff)[_i]), (LAS unsigned*)(lds + (bufoff) + ldsw + _i * 8192), 16, 0, 0); } while (0)
; #define PG8_MMA(ai, bj, At, Bt) do { __builtin_amdgcn_s_setprio(1); _Pragma("unroll") for (int m = 0; m < 4; ++m) _Pragma("unroll") for (int n = 0; n < 2; ++n) _Pragma("unroll") for (int k = 0; k < 2; ++k) \
;         acc[ai][bj][m][n] = __builtin_amdgcn_mfma_f32_16x16x32_bf16(Bt[n][k], At[m][k], acc[ai][bj][m][n], 0, 0, 0); __builtin_amdgcn_s_setprio(0); } while (0)
; #define PG8_WAIT_V(n) asm volatile("s_waitcnt vmcnt(" #n ")" ::: "memory")
; #define PG8_WAIT_L(n) asm volatile("s_waitcnt lgkmcnt(" #n ")" ::: "memory")
; #define PG8_BAR __builtin_amdgcn_s_barrier()
; template <class Epi>
; __device__ __forceinline__ void gemm_phase(LAS unsigned char* lds, const Gemm g, const StaticOrder& S, const Epi& E) {
;     ...
;             PG8_BAR; PG8_WAIT_L(0); PG8_MMA(1, 0, At, B0); PG8_BAR; PG8_SCHED;
;             PG8_STAGE(PG8_SB(1, 1), b3 + hstepB, voffB);
;             PG8_WAIT_V(6); PG8_BAR; PG8_MMA(1, 1, At, B1); PG8_BAR;
;         }
;         if (!lastpass) { E.mid(acc, cur, wr, wc, fr, fq); cA = nA; cB = nB; }
;     __device__ __forceinline__ void mid(f32x4 (&acc)[2][2][4][2], const pg8::Unit& u, int wr, int wc, int fr_in, int fq_in) const {
;         int fr = fr_in, fq = fq_in; asm volatile("" : "+v"(fr), "+v"(fq));
;         const int row0 = u.pm * 256 + wr * 64 + fr, col0 = u.pn * 256 + wc * 32 + 8 * fq;
; #pragma unroll
;         for (int i = 0; i < 16; ++i) { const int ai = i >> 3, m = (i >> 1) & 3, bj = i & 1; const int n = col0 + bj * 128;
;             const u32x4 gq = *(const u32x4*)(proj + (size_t)(row0 + ai * 128 + m * 16) * NC1 + C_MG + (n >> 7) * 256 + (n & 127));
;             acc[ai][bj][m][0][0] *= bf_lo(gq.x); acc[ai][bj][m][0][1] *= bf_hi(gq.x); acc[ai][bj][m][0][2] *= bf_lo(gq.y); acc[ai][bj][m][0][3] *= bf_hi(gq.y);
;             acc[ai][bj][m][1][0] *= bf_lo(gq.z); acc[ai][bj][m][1][1] *= bf_hi(gq.z); acc[ai][bj][m][1][2] *= bf_lo(gq.w); acc[ai][bj][m][1][3] *= bf_hi(gq.w); }
	s_waitcnt lgkmcnt(0)
	s_waitcnt lgkmcnt(0)
	v_mfma_f32_16x16x32_bf16 v[92:95], v[132:135], v[148:151], v[92:95]
	v_mfma_f32_16x16x32_bf16 v[88:91], v[140:143], v[148:151], v[88:91]
	v_mfma_f32_16x16x32_bf16 v[84:87], v[132:135], v[156:159], v[84:87]
	v_mfma_f32_16x16x32_bf16 v[80:83], v[140:143], v[156:159], v[80:83]
	v_mfma_f32_16x16x32_bf16 v[76:79], v[132:135], v[164:167], v[76:79]
	v_mfma_f32_16x16x32_bf16 v[72:75], v[140:143], v[164:167], v[72:75]
	v_mfma_f32_16x16x32_bf16 v[68:71], v[132:135], v[172:175], v[68:71]
	v_mfma_f32_16x16x32_bf16 v[64:67], v[140:143], v[172:175], v[64:67]
	v_mfma_f32_16x16x32_bf16 v[92:95], v[136:139], v[152:155], v[92:95]
	v_mfma_f32_16x16x32_bf16 v[88:91], v[144:147], v[152:155], v[88:91]
	v_mfma_f32_16x16x32_bf16 v[84:87], v[136:139], v[160:163], v[84:87]
	v_mfma_f32_16x16x32_bf16 v[80:83], v[144:147], v[160:163], v[80:83]
	v_mfma_f32_16x16x32_bf16 v[76:79], v[136:139], v[168:171], v[76:79]
	v_mfma_f32_16x16x32_bf16 v[72:75], v[144:147], v[168:171], v[72:75]
	v_mfma_f32_16x16x32_bf16 v[68:71], v[136:139], v[192:195], v[68:71]
	v_mfma_f32_16x16x32_bf16 v[64:67], v[144:147], v[192:195], v[64:67]
	s_barrier
	s_add_u32 s10, s66, 0x40080
	s_addc_u32 s11, s67, 0
	s_add_i32 s40, s41, s57
	s_mov_b32 m0, s40
	s_nop 0
	global_load_lds_dwordx4 v182, s[10:11]
	s_add_i32 m0, s40, 0x2000
	s_nop 0
	global_load_lds_dwordx4 v186, s[10:11]
	s_waitcnt vmcnt(6)
	s_barrier
	v_mfma_f32_16x16x32_bf16 v[28:31], v[196:199], v[148:151], v[28:31]
	v_mfma_f32_16x16x32_bf16 v[24:27], v[204:207], v[148:151], v[24:27]
	v_mfma_f32_16x16x32_bf16 v[20:23], v[196:199], v[156:159], v[20:23]
	v_mfma_f32_16x16x32_bf16 v[16:19], v[204:207], v[156:159], v[16:19]
	v_mfma_f32_16x16x32_bf16 v[12:15], v[196:199], v[164:167], v[12:15]
	v_mfma_f32_16x16x32_bf16 v[8:11], v[204:207], v[164:167], v[8:11]
	v_mfma_f32_16x16x32_bf16 v[4:7], v[196:199], v[172:175], v[4:7]
	v_mfma_f32_16x16x32_bf16 v[0:3], v[204:207], v[172:175], v[0:3]
	v_mfma_f32_16x16x32_bf16 v[28:31], v[200:203], v[152:155], v[28:31]
	v_mfma_f32_16x16x32_bf16 v[24:27], v[208:211], v[152:155], v[24:27]
	v_mfma_f32_16x16x32_bf16 v[20:23], v[200:203], v[160:163], v[20:23]
	v_mfma_f32_16x16x32_bf16 v[16:19], v[208:211], v[160:163], v[16:19]
	v_mfma_f32_16x16x32_bf16 v[12:15], v[200:203], v[168:171], v[12:15]
	v_mfma_f32_16x16x32_bf16 v[8:11], v[208:211], v[168:171], v[8:11]
	v_mfma_f32_16x16x32_bf16 v[4:7], v[200:203], v[192:195], v[4:7]
	v_mfma_f32_16x16x32_bf16 v[0:3], v[208:211], v[192:195], v[0:3]
	s_add_i32 s77, s77, 2
	s_add_u32 s64, s64, 0x100
	s_addc_u32 s65, s65, 0
	s_cmp_gt_u32 s77, 13
	s_barrier
	s_cbranch_scc0 .LBB0_302
	s_add_u32 s64, vcc_lo, 0xffffff00
	s_addc_u32 s65, vcc_hi, -1
	s_and_b64 vcc, exec, s[62:63]
	s_cbranch_vccz .LBB0_300
	v_mov_b32_e32 v128, v251
	v_mov_b32_e32 v129, v179
	v_mov_b64_e32 v[130:131], s[98:99]
	v_lshl_add_u32 v128, v128, 3, s16
	v_lshlrev_b32_e32 v132, 1, v128
	v_add_u32_e32 v134, s15, v129
	v_and_b32_e32 v140, 0xffffff00, v132
	v_and_b32_e32 v135, 0x78, v128
	v_mad_i64_i32 v[128:129], s[10:11], v134, s22, v[130:131]
	v_ashrrev_i32_e32 v141, 31, v140
	v_lshl_add_u64 v[128:129], v[128:129], 0, s[34:35]
	v_lshlrev_b64 v[132:133], 1, v[140:141]
	v_lshlrev_b32_e32 v176, 1, v135
	v_lshl_add_u64 v[128:129], v[128:129], 0, v[132:133]
	v_lshl_add_u64 v[128:129], v[128:129], 0, v[176:177]
	s_mov_b64 s[64:65], s[44:45]
	s_mov_b64 s[46:47], s[0:1]
	s_mov_b64 s[100:101], 0x50000
	global_load_dwordx4 v[132:135], v[128:129], off
	global_load_dwordx4 v[136:139], v[128:129], off offset:512
	v_lshl_add_u64 v[130:131], v[128:129], 0, s[100:101]
	global_load_dwordx4 v[140:143], v[130:131], off
	global_load_dwordx4 v[144:147], v[130:131], off offset:512
	v_lshl_add_u64 v[130:131], v[130:131], 0, s[100:101]
	global_load_dwordx4 v[148:151], v[130:131], off
	global_load_dwordx4 v[152:155], v[130:131], off offset:512
	v_lshl_add_u64 v[130:131], v[130:131], 0, s[100:101]
	global_load_dwordx4 v[156:159], v[130:131], off
	global_load_dwordx4 v[160:163], v[130:131], off offset:512
	s_mov_b64 s[100:101], 0x280000
	v_lshl_add_u64 v[130:131], v[128:129], 0, s[100:101]
	s_mov_b64 s[100:101], 0x50000
	global_load_dwordx4 v[164:167], v[130:131], off
	global_load_dwordx4 v[168:171], v[130:131], off offset:512
	v_lshl_add_u64 v[130:131], v[130:131], 0, s[100:101]
	global_load_dwordx4 v[172:175], v[130:131], off
	global_load_dwordx4 v[192:195], v[130:131], off offset:512
	v_lshl_add_u64 v[130:131], v[130:131], 0, s[100:101]
	global_load_dwordx4 v[196:199], v[130:131], off
	global_load_dwordx4 v[200:203], v[130:131], off offset:512
	v_lshl_add_u64 v[130:131], v[130:131], 0, s[100:101]
	global_load_dwordx4 v[204:207], v[130:131], off
	global_load_dwordx4 v[208:211], v[130:131], off offset:512
	s_waitcnt vmcnt(15)
	v_lshlrev_b32_e32 v128, 16, v132
	v_and_b32_e32 v129, 0xffff0000, v132
	v_lshlrev_b32_e32 v130, 16, v133
	v_and_b32_e32 v131, 0xffff0000, v133
	v_pk_mul_f32 v[124:125], v[124:125], v[128:129]
	v_pk_mul_f32 v[126:127], v[126:127], v[130:131]
	v_lshlrev_b32_e32 v128, 16, v134
	v_and_b32_e32 v129, 0xffff0000, v134
	v_lshlrev_b32_e32 v130, 16, v135
	v_and_b32_e32 v131, 0xffff0000, v135
	v_pk_mul_f32 v[120:121], v[120:121], v[128:129]
	v_pk_mul_f32 v[122:123], v[122:123], v[130:131]
	s_waitcnt vmcnt(14)
	v_lshlrev_b32_e32 v128, 16, v136
	v_and_b32_e32 v129, 0xffff0000, v136
	v_lshlrev_b32_e32 v130, 16, v137
	v_and_b32_e32 v131, 0xffff0000, v137
	v_pk_mul_f32 v[60:61], v[60:61], v[128:129]
	v_pk_mul_f32 v[62:63], v[62:63], v[130:131]
	v_lshlrev_b32_e32 v128, 16, v138
	v_and_b32_e32 v129, 0xffff0000, v138
	v_lshlrev_b32_e32 v130, 16, v139
	v_and_b32_e32 v131, 0xffff0000, v139
	v_pk_mul_f32 v[56:57], v[56:57], v[128:129]
	v_pk_mul_f32 v[58:59], v[58:59], v[130:131]
	s_waitcnt vmcnt(13)
; __device__ __forceinline__ float bf_lo(unsigned u) { return __uint_as_float(u << 16); }
; __device__ __forceinline__ float bf_hi(unsigned u) { return __uint_as_float(u & 0xffff0000u); }
;     __device__ __forceinline__ void mid(f32x4 (&acc)[2][2][4][2], const pg8::Unit& u, int wr, int wc, int fr_in, int fq_in) const {
;     ...
;         for (int i = 0; i < 16; ++i) { const int ai = i >> 3, m = (i >> 1) & 3, bj = i & 1; const int n = col0 + bj * 128;
;             const u32x4 gq = *(const u32x4*)(proj + (size_t)(row0 + ai * 128 + m * 16) * NC1 + C_MG + (n >> 7) * 256 + (n & 127));
;             acc[ai][bj][m][0][0] *= bf_lo(gq.x); acc[ai][bj][m][0][1] *= bf_hi(gq.x); acc[ai][bj][m][0][2] *= bf_lo(gq.y); acc[ai][bj][m][0][3] *= bf_hi(gq.y);
;             acc[ai][bj][m][1][0] *= bf_lo(gq.z); acc[ai][bj][m][1][1] *= bf_hi(gq.z); acc[ai][bj][m][1][2] *= bf_lo(gq.w); acc[ai][bj][m][1][3] *= bf_hi(gq.w); }
	v_lshlrev_b32_e32 v128, 16, v140
	v_and_b32_e32 v129, 0xffff0000, v140
	v_lshlrev_b32_e32 v130, 16, v141
	v_and_b32_e32 v131, 0xffff0000, v141
	v_pk_mul_f32 v[116:117], v[116:117], v[128:129]
	v_pk_mul_f32 v[118:119], v[118:119], v[130:131]
	v_lshlrev_b32_e32 v128, 16, v142
	v_and_b32_e32 v129, 0xffff0000, v142
	v_lshlrev_b32_e32 v130, 16, v143
	v_and_b32_e32 v131, 0xffff0000, v143
	v_pk_mul_f32 v[112:113], v[112:113], v[128:129]
	v_pk_mul_f32 v[114:115], v[114:115], v[130:131]
	s_waitcnt vmcnt(12)
	v_lshlrev_b32_e32 v128, 16, v144
	v_and_b32_e32 v129, 0xffff0000, v144
	v_lshlrev_b32_e32 v130, 16, v145
	v_and_b32_e32 v131, 0xffff0000, v145
	v_pk_mul_f32 v[52:53], v[52:53], v[128:129]
	v_pk_mul_f32 v[54:55], v[54:55], v[130:131]
	v_lshlrev_b32_e32 v128, 16, v146
	v_and_b32_e32 v129, 0xffff0000, v146
	v_lshlrev_b32_e32 v130, 16, v147
	v_and_b32_e32 v131, 0xffff0000, v147
	v_pk_mul_f32 v[48:49], v[48:49], v[128:129]
	v_pk_mul_f32 v[50:51], v[50:51], v[130:131]
	s_waitcnt vmcnt(11)
	v_lshlrev_b32_e32 v128, 16, v148
	v_and_b32_e32 v129, 0xffff0000, v148
	v_lshlrev_b32_e32 v130, 16, v149
	v_and_b32_e32 v131, 0xffff0000, v149
	v_pk_mul_f32 v[108:109], v[108:109], v[128:129]
	v_pk_mul_f32 v[110:111], v[110:111], v[130:131]
	v_lshlrev_b32_e32 v128, 16, v150
	v_and_b32_e32 v129, 0xffff0000, v150
	v_lshlrev_b32_e32 v130, 16, v151
	v_and_b32_e32 v131, 0xffff0000, v151
	v_pk_mul_f32 v[104:105], v[104:105], v[128:129]
	v_pk_mul_f32 v[106:107], v[106:107], v[130:131]
	s_waitcnt vmcnt(10)
	v_lshlrev_b32_e32 v128, 16, v152
	v_and_b32_e32 v129, 0xffff0000, v152
	v_lshlrev_b32_e32 v130, 16, v153
	v_and_b32_e32 v131, 0xffff0000, v153
	v_pk_mul_f32 v[44:45], v[44:45], v[128:129]
	v_pk_mul_f32 v[46:47], v[46:47], v[130:131]
	v_lshlrev_b32_e32 v128, 16, v154
	v_and_b32_e32 v129, 0xffff0000, v154
	v_lshlrev_b32_e32 v130, 16, v155
	v_and_b32_e32 v131, 0xffff0000, v155
	v_pk_mul_f32 v[40:41], v[40:41], v[128:129]
	v_pk_mul_f32 v[42:43], v[42:43], v[130:131]
	s_waitcnt vmcnt(9)
	v_lshlrev_b32_e32 v128, 16, v156
	v_and_b32_e32 v129, 0xffff0000, v156
	v_lshlrev_b32_e32 v130, 16, v157
	v_and_b32_e32 v131, 0xffff0000, v157
	v_pk_mul_f32 v[100:101], v[100:101], v[128:129]
	v_pk_mul_f32 v[102:103], v[102:103], v[130:131]
	v_lshlrev_b32_e32 v128, 16, v158
	v_and_b32_e32 v129, 0xffff0000, v158
	v_lshlrev_b32_e32 v130, 16, v159
	v_and_b32_e32 v131, 0xffff0000, v159
	v_pk_mul_f32 v[96:97], v[96:97], v[128:129]
	v_pk_mul_f32 v[98:99], v[98:99], v[130:131]
	s_waitcnt vmcnt(8)
	v_lshlrev_b32_e32 v128, 16, v160
	v_and_b32_e32 v129, 0xffff0000, v160
	v_lshlrev_b32_e32 v130, 16, v161
	v_and_b32_e32 v131, 0xffff0000, v161
	v_pk_mul_f32 v[36:37], v[36:37], v[128:129]
	v_pk_mul_f32 v[38:39], v[38:39], v[130:131]
	v_lshlrev_b32_e32 v128, 16, v162
	v_and_b32_e32 v129, 0xffff0000, v162
	v_lshlrev_b32_e32 v130, 16, v163
	v_and_b32_e32 v131, 0xffff0000, v163
	v_pk_mul_f32 v[32:33], v[32:33], v[128:129]
	v_pk_mul_f32 v[34:35], v[34:35], v[130:131]
	s_waitcnt vmcnt(7)
	v_lshlrev_b32_e32 v128, 16, v164
	v_and_b32_e32 v129, 0xffff0000, v164
	v_lshlrev_b32_e32 v130, 16, v165
	v_and_b32_e32 v131, 0xffff0000, v165
	v_pk_mul_f32 v[92:93], v[92:93], v[128:129]
	v_pk_mul_f32 v[94:95], v[94:95], v[130:131]
	v_lshlrev_b32_e32 v128, 16, v166
	v_and_b32_e32 v129, 0xffff0000, v166
	v_lshlrev_b32_e32 v130, 16, v167
	v_and_b32_e32 v131, 0xffff0000, v167
	v_pk_mul_f32 v[88:89], v[88:89], v[128:129]
	v_pk_mul_f32 v[90:91], v[90:91], v[130:131]
	s_waitcnt vmcnt(6)
	v_lshlrev_b32_e32 v128, 16, v168
	v_and_b32_e32 v129, 0xffff0000, v168
	v_lshlrev_b32_e32 v130, 16, v169
	v_and_b32_e32 v131, 0xffff0000, v169
	v_pk_mul_f32 v[28:29], v[28:29], v[128:129]
	v_pk_mul_f32 v[30:31], v[30:31], v[130:131]
	v_lshlrev_b32_e32 v128, 16, v170
	v_and_b32_e32 v129, 0xffff0000, v170
	v_lshlrev_b32_e32 v130, 16, v171
	v_and_b32_e32 v131, 0xffff0000, v171
	v_pk_mul_f32 v[24:25], v[24:25], v[128:129]
	v_pk_mul_f32 v[26:27], v[26:27], v[130:131]
	s_waitcnt vmcnt(5)
	v_lshlrev_b32_e32 v128, 16, v172
	v_and_b32_e32 v129, 0xffff0000, v172
	v_lshlrev_b32_e32 v130, 16, v173
	v_and_b32_e32 v131, 0xffff0000, v173
	v_pk_mul_f32 v[84:85], v[84:85], v[128:129]
	v_pk_mul_f32 v[86:87], v[86:87], v[130:131]
	v_lshlrev_b32_e32 v128, 16, v174
	v_and_b32_e32 v129, 0xffff0000, v174
	v_lshlrev_b32_e32 v130, 16, v175
	v_and_b32_e32 v131, 0xffff0000, v175
	v_pk_mul_f32 v[80:81], v[80:81], v[128:129]
	v_pk_mul_f32 v[82:83], v[82:83], v[130:131]
	s_waitcnt vmcnt(4)
	v_lshlrev_b32_e32 v128, 16, v192
	v_and_b32_e32 v129, 0xffff0000, v192
	v_lshlrev_b32_e32 v130, 16, v193
	v_and_b32_e32 v131, 0xffff0000, v193
	v_pk_mul_f32 v[20:21], v[20:21], v[128:129]
	v_pk_mul_f32 v[22:23], v[22:23], v[130:131]
	v_lshlrev_b32_e32 v128, 16, v194
	v_and_b32_e32 v129, 0xffff0000, v194
	v_lshlrev_b32_e32 v130, 16, v195
	v_and_b32_e32 v131, 0xffff0000, v195
	v_pk_mul_f32 v[16:17], v[16:17], v[128:129]
	v_pk_mul_f32 v[18:19], v[18:19], v[130:131]
	s_waitcnt vmcnt(3)
	v_lshlrev_b32_e32 v128, 16, v196
	v_and_b32_e32 v129, 0xffff0000, v196
	v_lshlrev_b32_e32 v130, 16, v197
	v_and_b32_e32 v131, 0xffff0000, v197
	v_pk_mul_f32 v[76:77], v[76:77], v[128:129]
	v_pk_mul_f32 v[78:79], v[78:79], v[130:131]
	v_lshlrev_b32_e32 v128, 16, v198
	v_and_b32_e32 v129, 0xffff0000, v198
	v_lshlrev_b32_e32 v130, 16, v199
	v_and_b32_e32 v131, 0xffff0000, v199
	v_pk_mul_f32 v[72:73], v[72:73], v[128:129]
	v_pk_mul_f32 v[74:75], v[74:75], v[130:131]
	s_waitcnt vmcnt(2)
	v_lshlrev_b32_e32 v128, 16, v200
	v_and_b32_e32 v129, 0xffff0000, v200
	v_lshlrev_b32_e32 v130, 16, v201
	v_and_b32_e32 v131, 0xffff0000, v201
	v_pk_mul_f32 v[12:13], v[12:13], v[128:129]
	v_pk_mul_f32 v[14:15], v[14:15], v[130:131]
	v_lshlrev_b32_e32 v128, 16, v202
	v_and_b32_e32 v129, 0xffff0000, v202
	v_lshlrev_b32_e32 v130, 16, v203
	v_and_b32_e32 v131, 0xffff0000, v203
	v_pk_mul_f32 v[8:9], v[8:9], v[128:129]
	v_pk_mul_f32 v[10:11], v[10:11], v[130:131]
	s_waitcnt vmcnt(1)
	v_lshlrev_b32_e32 v128, 16, v204
	v_and_b32_e32 v129, 0xffff0000, v204
	v_lshlrev_b32_e32 v130, 16, v205
	v_and_b32_e32 v131, 0xffff0000, v205
	v_pk_mul_f32 v[68:69], v[68:69], v[128:129]
	v_pk_mul_f32 v[70:71], v[70:71], v[130:131]
	v_lshlrev_b32_e32 v128, 16, v206
	v_and_b32_e32 v129, 0xffff0000, v206
	v_lshlrev_b32_e32 v130, 16, v207
	v_and_b32_e32 v131, 0xffff0000, v207
	v_pk_mul_f32 v[64:65], v[64:65], v[128:129]
	v_pk_mul_f32 v[66:67], v[66:67], v[130:131]
	s_waitcnt vmcnt(0)
	v_lshlrev_b32_e32 v128, 16, v208
	v_and_b32_e32 v129, 0xffff0000, v208
	v_lshlrev_b32_e32 v130, 16, v209
	v_and_b32_e32 v131, 0xffff0000, v209
	v_pk_mul_f32 v[4:5], v[4:5], v[128:129]
	v_pk_mul_f32 v[6:7], v[6:7], v[130:131]
	v_lshlrev_b32_e32 v128, 16, v210
	v_and_b32_e32 v129, 0xffff0000, v210
	v_lshlrev_b32_e32 v130, 16, v211
	v_and_b32_e32 v131, 0xffff0000, v211
	v_pk_mul_f32 v[0:1], v[0:1], v[128:129]
	v_pk_mul_f32 v[2:3], v[2:3], v[130:131]
	s_branch .LBB0_300

; #define PG8_WAIT_V(n) asm volatile("s_waitcnt vmcnt(" #n ")" ::: "memory")
; #define PG8_BAR __builtin_amdgcn_s_barrier()
; template <class Epi>
; __device__ __forceinline__ void gemm_phase(LAS unsigned char* lds, const Gemm g, const StaticOrder& S, const Epi& E) {
;     ...
;     PG8_WAIT_V(0);
;     if (wr == 0) PG8_BAR;
;     PG8_BAR;
.LBB0_584:
	s_setprio 0
	s_waitcnt vmcnt(0)
	v_readlane_b32 s0, v255, 42
	s_cmpk_gt_u32 s0, 0xff
	s_cbranch_scc1 .LBB0_586
	s_barrier
